# attention: drop dead rescale check after step barrier and add-zero in steady loops
# speedup vs baseline: 1.0382x; 1.0119x over previous
.LBB0_798:
	v_bfe_i32 v196, v132, 0, 1
	v_add_u32_e32 v197, s10, v219
	ds_read_b64_tr_b16 v[184:185], v197 offset:24576
	ds_read_b64_tr_b16 v[186:187], v197 offset:25088
	s_waitcnt lgkmcnt(9)
	v_mfma_f32_32x32x16_bf16 v[100:115], v[180:183], v[116:119], v[36:51]
	v_add_f32_e32 v84, v68, v69
	v_add_f32_e32 v84, v70, v84
	v_add_f32_e32 v84, v71, v84
	v_cvt_pk_bf16_f32 v68, v68, v69
	v_add_f32_e32 v84, v72, v84
	v_and_b32_e32 v148, v68, v196
	v_cvt_pk_bf16_f32 v68, v70, v71
	v_add_f32_e32 v84, v73, v84
	v_and_b32_e32 v149, v68, v196
	ds_read_b64_tr_b16 v[180:181], v197 offset:28672
	ds_read_b64_tr_b16 v[182:183], v197 offset:29184
	v_add_f32_e32 v68, v74, v84
	s_waitcnt lgkmcnt(10)
	v_mfma_f32_32x32x16_bf16 v[84:99], v[176:179], v[116:119], v[36:51]
	v_add_f32_e32 v68, v75, v68
	v_add_f32_e32 v68, v76, v68
	v_add_f32_e32 v136, v77, v68
	v_cvt_pk_bf16_f32 v68, v72, v73
	v_and_b32_e32 v150, v68, v196
	v_cvt_pk_bf16_f32 v68, v74, v75
	v_and_b32_e32 v151, v68, v196
	ds_read_b64_tr_b16 v[68:69], v197 offset:25600
	ds_read_b64_tr_b16 v[70:71], v197 offset:26112
	s_waitcnt lgkmcnt(11)
	v_mfma_f32_32x32x16_bf16 v[100:115], v[172:175], v[120:123], v[100:115]
	v_add_f32_e32 v72, v78, v136
	v_add_f32_e32 v72, v79, v72
	v_add_f32_e32 v72, v80, v72
	v_add_f32_e32 v136, v81, v72
	v_cvt_pk_bf16_f32 v72, v76, v77
	v_and_b32_e32 v144, v72, v196
	v_cvt_pk_bf16_f32 v72, v78, v79
	v_and_b32_e32 v145, v72, v196
	ds_read_b64_tr_b16 v[72:73], v197 offset:29696
	ds_read_b64_tr_b16 v[74:75], v197 offset:30208
	s_waitcnt lgkmcnt(12)
	v_mfma_f32_32x32x16_bf16 v[84:99], v[168:171], v[120:123], v[84:99]
	v_add_f32_e32 v76, v82, v136
	v_add_f32_e32 v76, v83, v76
	v_add_f32_e32 v76, v52, v76
	v_add_f32_e32 v136, v53, v76
	v_cvt_pk_bf16_f32 v76, v80, v81
	v_and_b32_e32 v146, v76, v196
	v_cvt_pk_bf16_f32 v76, v82, v83
	v_and_b32_e32 v147, v76, v196
	ds_read_b64_tr_b16 v[76:77], v197 offset:26624
	ds_read_b64_tr_b16 v[78:79], v197 offset:27136
	s_waitcnt lgkmcnt(13)
	v_mfma_f32_32x32x16_bf16 v[100:115], v[164:167], v[124:127], v[100:115]
	v_add_f32_e32 v80, v54, v136
	v_add_f32_e32 v80, v55, v80
	v_cvt_pk_bf16_f32 v52, v52, v53
	v_add_f32_e32 v80, v56, v80
	v_and_b32_e32 v140, v52, v196
	v_cvt_pk_bf16_f32 v52, v54, v55
	v_add_f32_e32 v80, v57, v80
	v_and_b32_e32 v141, v52, v196
	ds_read_b64_tr_b16 v[52:53], v197 offset:30720
	ds_read_b64_tr_b16 v[54:55], v197 offset:31232
	s_waitcnt lgkmcnt(14)
	v_mfma_f32_32x32x16_bf16 v[84:99], v[160:163], v[124:127], v[84:99]
	v_add_f32_e32 v80, v58, v80
	v_add_f32_e32 v80, v59, v80
	v_cvt_pk_bf16_f32 v56, v56, v57
	v_add_f32_e32 v80, v60, v80
	v_and_b32_e32 v142, v56, v196
	v_cvt_pk_bf16_f32 v56, v58, v59
	v_add_f32_e32 v80, v61, v80
	v_and_b32_e32 v143, v56, v196
	ds_read_b64_tr_b16 v[56:57], v197 offset:27648
	ds_read_b64_tr_b16 v[58:59], v197 offset:28160
	s_waitcnt lgkmcnt(14)
	v_mfma_f32_32x32x16_bf16 v[100:115], v[156:159], v[128:131], v[100:115]
	v_add_f32_e32 v80, v62, v80
	v_add_f32_e32 v80, v63, v80
	v_cvt_pk_bf16_f32 v60, v60, v61
	v_add_f32_e32 v80, v64, v80
	v_and_b32_e32 v136, v60, v196
	v_cvt_pk_bf16_f32 v60, v62, v63
	v_add_f32_e32 v80, v65, v80
	v_and_b32_e32 v137, v60, v196
	ds_read_b64_tr_b16 v[60:61], v197 offset:31744
	ds_read_b64_tr_b16 v[62:63], v197 offset:32256
	v_mfma_f32_32x32x16_bf16 v[84:99], v[152:155], v[128:131], v[84:99]
	v_add_f32_e32 v80, v66, v80
	v_cvt_pk_bf16_f32 v64, v64, v65
	v_add_f32_e32 v80, v67, v80
	v_and_b32_e32 v138, v64, v196
	v_cvt_pk_bf16_f32 v64, v66, v67
	v_and_b32_e32 v139, v64, v196
	s_mov_b32 s22, 0xfffe0000
	s_mov_b32 s23, -1
	v_lshl_add_u64 v[64:65], v[194:195], 0, s[22:23]
	s_add_i32 s10, s25, s46
	s_mov_b32 s11, m0
	s_mov_b32 m0, s10
	s_nop 0
	global_load_lds_dwordx4 v[64:65], off
	s_mov_b32 m0, s11
	v_lshl_add_u64 v[64:65], v[192:193], 0, s[22:23]
	s_add_i32 s10, s24, s47
	s_mov_b32 s11, m0
	s_mov_b32 m0, s10
	s_nop 0
	global_load_lds_dwordx4 v[64:65], off
	s_mov_b32 m0, s11
	v_and_b32_e32 v66, v80, v196
	v_add_f32_e32 v204, v220, v66

.LBB0_801:
	s_add_i32 s10, s24, 0x2000
	s_cmpk_lg_i32 s24, 0x4000
	v_alignbit_b32 v132, v133, v132, 1
	s_cselect_b32 s54, s10, 0
	v_bfe_i32 v196, v132, 0, 1
	v_add_u32_e32 v197, s25, v219
	ds_read_b64_tr_b16 v[152:153], v197 offset:24576
	ds_read_b64_tr_b16 v[154:155], v197 offset:25088
	s_waitcnt lgkmcnt(9)
	v_mfma_f32_32x32x16_bf16 v[68:83], v[64:67], v[116:119], v[36:51]
	v_add_f32_e32 v52, v100, v101
	v_add_f32_e32 v52, v102, v52
	v_add_f32_e32 v52, v103, v52
	v_cvt_pk_bf16_f32 v53, v100, v101
	v_add_f32_e32 v52, v104, v52
	v_and_b32_e32 v148, v53, v196
	v_cvt_pk_bf16_f32 v53, v102, v103
	v_add_f32_e32 v52, v105, v52
	v_and_b32_e32 v149, v53, v196
	ds_read_b64_tr_b16 v[156:157], v197 offset:28672
	ds_read_b64_tr_b16 v[158:159], v197 offset:29184
	v_add_f32_e32 v52, v106, v52
	v_add_f32_e32 v52, v107, v52
	v_add_f32_e32 v52, v108, v52
	v_add_f32_e32 v136, v109, v52
	s_waitcnt lgkmcnt(10)
	v_mfma_f32_32x32x16_bf16 v[52:67], v[180:183], v[116:119], v[36:51]
	v_cvt_pk_bf16_f32 v100, v104, v105
	v_and_b32_e32 v150, v100, v196
	v_cvt_pk_bf16_f32 v100, v106, v107
	v_and_b32_e32 v151, v100, v196
	ds_read_b64_tr_b16 v[100:101], v197 offset:25600
	ds_read_b64_tr_b16 v[102:103], v197 offset:26112
	s_waitcnt lgkmcnt(11)
	v_mfma_f32_32x32x16_bf16 v[68:83], v[184:187], v[120:123], v[68:83]
	v_add_f32_e32 v104, v110, v136
	v_add_f32_e32 v104, v111, v104
	v_add_f32_e32 v104, v112, v104
	v_add_f32_e32 v136, v113, v104
	v_cvt_pk_bf16_f32 v104, v108, v109
	v_and_b32_e32 v144, v104, v196
	v_cvt_pk_bf16_f32 v104, v110, v111
	v_and_b32_e32 v145, v104, v196
	ds_read_b64_tr_b16 v[104:105], v197 offset:29696
	ds_read_b64_tr_b16 v[106:107], v197 offset:30208
	s_waitcnt lgkmcnt(12)
	v_mfma_f32_32x32x16_bf16 v[52:67], v[176:179], v[120:123], v[52:67]
	v_add_f32_e32 v108, v114, v136
	v_add_f32_e32 v108, v115, v108
	v_add_f32_e32 v108, v84, v108
	v_add_f32_e32 v136, v85, v108
	v_cvt_pk_bf16_f32 v108, v112, v113
	v_and_b32_e32 v146, v108, v196
	v_cvt_pk_bf16_f32 v108, v114, v115
	v_and_b32_e32 v147, v108, v196
	ds_read_b64_tr_b16 v[108:109], v197 offset:26624
	ds_read_b64_tr_b16 v[110:111], v197 offset:27136
	s_waitcnt lgkmcnt(13)
	v_mfma_f32_32x32x16_bf16 v[68:83], v[172:175], v[124:127], v[68:83]
	v_add_f32_e32 v112, v86, v136
	v_add_f32_e32 v112, v87, v112
	v_cvt_pk_bf16_f32 v84, v84, v85
	v_add_f32_e32 v112, v88, v112
	v_and_b32_e32 v140, v84, v196
	v_cvt_pk_bf16_f32 v84, v86, v87
	v_add_f32_e32 v112, v89, v112
	v_and_b32_e32 v141, v84, v196
	ds_read_b64_tr_b16 v[84:85], v197 offset:30720
	ds_read_b64_tr_b16 v[86:87], v197 offset:31232
	s_waitcnt lgkmcnt(14)
	v_mfma_f32_32x32x16_bf16 v[52:67], v[168:171], v[124:127], v[52:67]
	v_add_f32_e32 v112, v90, v112
	v_add_f32_e32 v112, v91, v112
	v_cvt_pk_bf16_f32 v88, v88, v89
	v_add_f32_e32 v112, v92, v112
	v_and_b32_e32 v142, v88, v196
	v_cvt_pk_bf16_f32 v88, v90, v91
	v_add_f32_e32 v112, v93, v112
	v_and_b32_e32 v143, v88, v196
	ds_read_b64_tr_b16 v[88:89], v197 offset:27648
	ds_read_b64_tr_b16 v[90:91], v197 offset:28160
	s_waitcnt lgkmcnt(14)
	v_mfma_f32_32x32x16_bf16 v[68:83], v[164:167], v[128:131], v[68:83]
	v_add_f32_e32 v112, v94, v112
	v_add_f32_e32 v112, v95, v112
	v_cvt_pk_bf16_f32 v92, v92, v93
	v_add_f32_e32 v112, v96, v112
	v_and_b32_e32 v136, v92, v196
	v_cvt_pk_bf16_f32 v92, v94, v95
	v_add_f32_e32 v112, v97, v112
	v_and_b32_e32 v137, v92, v196
	ds_read_b64_tr_b16 v[92:93], v197 offset:31744
	ds_read_b64_tr_b16 v[94:95], v197 offset:32256
	v_mfma_f32_32x32x16_bf16 v[52:67], v[160:163], v[128:131], v[52:67]
	v_add_f32_e32 v112, v98, v112
	v_cvt_pk_bf16_f32 v96, v96, v97
	v_add_f32_e32 v112, v99, v112
	v_and_b32_e32 v138, v96, v196
	v_cvt_pk_bf16_f32 v96, v98, v99
	v_and_b32_e32 v139, v96, v196
	v_and_b32_e32 v96, v112, v196
	v_add_f32_e32 v220, v204, v96
	s_add_i32 s10, s24, s46
	s_mov_b32 s11, m0
	s_mov_b32 m0, s10
	s_nop 0
	global_load_lds_dwordx4 v[194:195], off
	s_mov_b32 m0, s11
	s_add_i32 s10, s54, s47
	s_mov_b32 s11, m0
	s_mov_b32 m0, s10
	s_nop 0
	global_load_lds_dwordx4 v[192:193], off
	s_mov_b32 m0, s11
.LBB0_802:
	s_waitcnt lgkmcnt(14)
	v_mfma_f32_32x32x16_bf16 v[20:35], v[148:151], v[152:155], v[20:35]
	v_exp_f32_e32 v68, v68
	v_exp_f32_e32 v69, v69
	v_exp_f32_e32 v70, v70
	v_exp_f32_e32 v71, v71
	s_waitcnt lgkmcnt(12)
	v_mfma_f32_32x32x16_bf16 v[4:19], v[148:151], v[156:159], v[4:19]
	v_exp_f32_e32 v72, v72
	v_exp_f32_e32 v73, v73
	v_exp_f32_e32 v74, v74
	v_exp_f32_e32 v75, v75
	v_add_u32_e32 v96, s54, v218
	ds_read_b128 v[180:183], v96
	ds_read_b128 v[176:179], v96 offset:512
	s_waitcnt lgkmcnt(12)
	v_mfma_f32_32x32x16_bf16 v[20:35], v[144:147], v[100:103], v[20:35]
	v_exp_f32_e32 v76, v76
	v_exp_f32_e32 v77, v77
	v_exp_f32_e32 v78, v78
	v_exp_f32_e32 v79, v79
	ds_read_b128 v[172:175], v96 offset:2048
	ds_read_b128 v[168:171], v96 offset:2560
	s_waitcnt lgkmcnt(12)
	v_mfma_f32_32x32x16_bf16 v[4:19], v[144:147], v[104:107], v[4:19]
	v_exp_f32_e32 v80, v80
	v_exp_f32_e32 v81, v81
	v_exp_f32_e32 v82, v82
	v_exp_f32_e32 v83, v83
	ds_read_b128 v[164:167], v96 offset:4096
	ds_read_b128 v[160:163], v96 offset:4608
	s_waitcnt lgkmcnt(12)
	v_mfma_f32_32x32x16_bf16 v[20:35], v[140:143], v[108:111], v[20:35]
	v_exp_f32_e32 v52, v52
	v_exp_f32_e32 v53, v53
	v_exp_f32_e32 v54, v54
	v_exp_f32_e32 v55, v55
	ds_read_b128 v[156:159], v96 offset:6144
	ds_read_b128 v[152:155], v96 offset:6656
	s_waitcnt lgkmcnt(12)
	v_mfma_f32_32x32x16_bf16 v[4:19], v[140:143], v[84:87], v[4:19]
	v_exp_f32_e32 v56, v56
	v_exp_f32_e32 v57, v57
	v_exp_f32_e32 v58, v58
	v_exp_f32_e32 v59, v59
	s_waitcnt lgkmcnt(10)
	v_mfma_f32_32x32x16_bf16 v[20:35], v[136:139], v[88:91], v[20:35]
	v_exp_f32_e32 v60, v60
	v_exp_f32_e32 v61, v61
	v_exp_f32_e32 v62, v62
	v_exp_f32_e32 v63, v63
	s_waitcnt lgkmcnt(8)
	v_mfma_f32_32x32x16_bf16 v[4:19], v[136:139], v[92:95], v[4:19]
	v_exp_f32_e32 v64, v64
	v_exp_f32_e32 v65, v65
	v_exp_f32_e32 v66, v66
	v_exp_f32_e32 v67, v67
	s_waitcnt vmcnt(2) lgkmcnt(0)
	s_barrier
.LBB0_804:
	s_add_i32 s0, s0, 2
	s_add_i32 s10, s54, 0x2000
	v_alignbit_b32 v84, v135, v134, 1
	v_alignbit_b32 v85, v134, v133, 1
	v_lshrrev_b32_e32 v86, 1, v135
	s_cmpk_lg_i32 s54, 0x4000
	v_alignbit_b32 v132, v85, v132, 1
	v_alignbit_b32 v133, v84, v85, 1
	v_alignbit_b32 v134, v86, v84, 1
	v_lshrrev_b32_e32 v135, 2, v135
	s_cselect_b32 s42, s10, 0
	v_lshl_add_u64 v[192:193], v[192:193], 0, s[80:81]
	s_cmp_ge_i32 s0, s1
	v_lshl_add_u64 v[194:195], v[194:195], 0, s[80:81]
	s_cbranch_scc1 .LBB0_813
	s_mov_b32 s10, s24
	s_mov_b32 s25, s54
	s_mov_b32 s24, s42
	s_branch .LBB0_798

.LBB0_815:
	v_bfe_i32 v188, v132, 0, 1
	v_add_u32_e32 v189, s24, v219
	ds_read_b64_tr_b16 v[184:185], v189 offset:24576
	ds_read_b64_tr_b16 v[186:187], v189 offset:25088
	s_waitcnt lgkmcnt(9)
	v_mfma_f32_32x32x16_bf16 v[100:115], v[180:183], v[116:119], v[36:51]
	v_add_f32_e32 v84, v68, v69
	v_add_f32_e32 v84, v70, v84
	v_add_f32_e32 v84, v71, v84
	v_cvt_pk_bf16_f32 v68, v68, v69
	v_add_f32_e32 v84, v72, v84
	v_and_b32_e32 v148, v68, v188
	v_cvt_pk_bf16_f32 v68, v70, v71
	v_add_f32_e32 v84, v73, v84
	v_and_b32_e32 v149, v68, v188
	ds_read_b64_tr_b16 v[180:181], v189 offset:28672
	ds_read_b64_tr_b16 v[182:183], v189 offset:29184
	v_add_f32_e32 v68, v74, v84
	s_waitcnt lgkmcnt(10)
	v_mfma_f32_32x32x16_bf16 v[84:99], v[176:179], v[116:119], v[36:51]
	v_add_f32_e32 v68, v75, v68
	v_add_f32_e32 v68, v76, v68
	v_add_f32_e32 v136, v77, v68
	v_cvt_pk_bf16_f32 v68, v72, v73
	v_and_b32_e32 v150, v68, v188
	v_cvt_pk_bf16_f32 v68, v74, v75
	v_and_b32_e32 v151, v68, v188
	ds_read_b64_tr_b16 v[68:69], v189 offset:25600
	ds_read_b64_tr_b16 v[70:71], v189 offset:26112
	s_waitcnt lgkmcnt(11)
	v_mfma_f32_32x32x16_bf16 v[100:115], v[172:175], v[120:123], v[100:115]
	v_add_f32_e32 v72, v78, v136
	v_add_f32_e32 v72, v79, v72
	v_add_f32_e32 v72, v80, v72
	v_add_f32_e32 v136, v81, v72
	v_cvt_pk_bf16_f32 v72, v76, v77
	v_and_b32_e32 v144, v72, v188
	v_cvt_pk_bf16_f32 v72, v78, v79
	v_and_b32_e32 v145, v72, v188
	ds_read_b64_tr_b16 v[72:73], v189 offset:29696
	ds_read_b64_tr_b16 v[74:75], v189 offset:30208
	s_waitcnt lgkmcnt(12)
	v_mfma_f32_32x32x16_bf16 v[84:99], v[168:171], v[120:123], v[84:99]
	v_add_f32_e32 v76, v82, v136
	v_add_f32_e32 v76, v83, v76
	v_add_f32_e32 v76, v52, v76
	v_add_f32_e32 v136, v53, v76
	v_cvt_pk_bf16_f32 v76, v80, v81
	v_and_b32_e32 v146, v76, v188
	v_cvt_pk_bf16_f32 v76, v82, v83
	v_and_b32_e32 v147, v76, v188
	ds_read_b64_tr_b16 v[76:77], v189 offset:26624
	ds_read_b64_tr_b16 v[78:79], v189 offset:27136
	s_waitcnt lgkmcnt(13)
	v_mfma_f32_32x32x16_bf16 v[100:115], v[164:167], v[124:127], v[100:115]
	v_add_f32_e32 v80, v54, v136
	v_add_f32_e32 v80, v55, v80
	v_cvt_pk_bf16_f32 v52, v52, v53
	v_add_f32_e32 v80, v56, v80
	v_and_b32_e32 v140, v52, v188
	v_cvt_pk_bf16_f32 v52, v54, v55
	v_add_f32_e32 v80, v57, v80
	v_and_b32_e32 v141, v52, v188
	ds_read_b64_tr_b16 v[52:53], v189 offset:30720
	ds_read_b64_tr_b16 v[54:55], v189 offset:31232
	s_waitcnt lgkmcnt(14)
	v_mfma_f32_32x32x16_bf16 v[84:99], v[160:163], v[124:127], v[84:99]
	v_add_f32_e32 v80, v58, v80
	v_add_f32_e32 v80, v59, v80
	v_cvt_pk_bf16_f32 v56, v56, v57
	v_add_f32_e32 v80, v60, v80
	v_and_b32_e32 v142, v56, v188
	v_cvt_pk_bf16_f32 v56, v58, v59
	v_add_f32_e32 v80, v61, v80
	v_and_b32_e32 v143, v56, v188
	ds_read_b64_tr_b16 v[56:57], v189 offset:27648
	ds_read_b64_tr_b16 v[58:59], v189 offset:28160
	s_waitcnt lgkmcnt(14)
	v_mfma_f32_32x32x16_bf16 v[100:115], v[156:159], v[128:131], v[100:115]
	v_add_f32_e32 v80, v62, v80
	v_add_f32_e32 v80, v63, v80
	v_cvt_pk_bf16_f32 v60, v60, v61
	v_add_f32_e32 v80, v64, v80
	v_and_b32_e32 v136, v60, v188
	v_cvt_pk_bf16_f32 v60, v62, v63
	v_add_f32_e32 v80, v65, v80
	v_and_b32_e32 v137, v60, v188
	ds_read_b64_tr_b16 v[60:61], v189 offset:31744
	ds_read_b64_tr_b16 v[62:63], v189 offset:32256
	v_mfma_f32_32x32x16_bf16 v[84:99], v[152:155], v[128:131], v[84:99]
	v_add_f32_e32 v80, v66, v80
	v_cvt_pk_bf16_f32 v64, v64, v65
	v_add_f32_e32 v80, v67, v80
	v_and_b32_e32 v138, v64, v188
	v_cvt_pk_bf16_f32 v64, v66, v67
	v_and_b32_e32 v139, v64, v188
	s_add_i32 s0, s25, 1
	s_cmp_ge_u32 s0, s48
	s_cselect_b64 s[10:11], -1, 0
	s_and_b64 vcc, exec, s[10:11]
	s_cbranch_vccnz .LBB0_817
	s_mov_b32 s22, 0xfffe0000
	s_mov_b32 s23, -1
	s_add_i32 s0, s54, s46
	v_lshl_add_u64 v[64:65], v[206:207], 0, s[22:23]
	s_mov_b32 s1, m0
	s_mov_b32 m0, s0
	s_nop 0
	global_load_lds_dwordx4 v[64:65], off
	s_mov_b32 m0, s1

.LBB0_824:
	v_alignbit_b32 v132, v133, v132, 1
	v_bfe_i32 v203, v132, 0, 1
	v_add_u32_e32 v196, s54, v219
	ds_read_b64_tr_b16 v[188:189], v196 offset:24576
	ds_read_b64_tr_b16 v[190:191], v196 offset:25088
	s_waitcnt lgkmcnt(9)
	v_mfma_f32_32x32x16_bf16 v[68:83], v[180:183], v[116:119], v[36:51]
	v_add_f32_e32 v52, v100, v101
	v_add_f32_e32 v52, v102, v52
	v_add_f32_e32 v52, v103, v52
	v_cvt_pk_bf16_f32 v53, v100, v101
	v_add_f32_e32 v52, v104, v52
	v_and_b32_e32 v148, v53, v203
	v_cvt_pk_bf16_f32 v53, v102, v103
	v_add_f32_e32 v52, v105, v52
	v_and_b32_e32 v149, v53, v203
	ds_read_b64_tr_b16 v[192:193], v196 offset:28672
	ds_read_b64_tr_b16 v[194:195], v196 offset:29184
	v_add_f32_e32 v52, v106, v52
	v_add_f32_e32 v52, v107, v52
	v_add_f32_e32 v52, v108, v52
	v_add_f32_e32 v100, v109, v52
	s_waitcnt lgkmcnt(10)
	v_mfma_f32_32x32x16_bf16 v[52:67], v[176:179], v[116:119], v[36:51]
	v_cvt_pk_bf16_f32 v101, v104, v105
	v_and_b32_e32 v150, v101, v203
	v_cvt_pk_bf16_f32 v101, v106, v107
	v_and_b32_e32 v151, v101, v203
	ds_read_b64_tr_b16 v[184:185], v196 offset:25600
	ds_read_b64_tr_b16 v[186:187], v196 offset:26112
	s_waitcnt lgkmcnt(11)
	v_mfma_f32_32x32x16_bf16 v[68:83], v[172:175], v[120:123], v[68:83]
	v_add_f32_e32 v100, v110, v100
	v_add_f32_e32 v100, v111, v100
	v_cvt_pk_bf16_f32 v101, v108, v109
	v_add_f32_e32 v100, v112, v100
	v_and_b32_e32 v144, v101, v203
	v_cvt_pk_bf16_f32 v101, v110, v111
	v_add_f32_e32 v100, v113, v100
	v_and_b32_e32 v145, v101, v203
	ds_read_b64_tr_b16 v[104:105], v196 offset:29696
	ds_read_b64_tr_b16 v[106:107], v196 offset:30208
	s_waitcnt lgkmcnt(12)
	v_mfma_f32_32x32x16_bf16 v[52:67], v[168:171], v[120:123], v[52:67]
	v_add_f32_e32 v100, v114, v100
	v_add_f32_e32 v100, v115, v100
	v_add_f32_e32 v100, v84, v100
	v_add_f32_e32 v108, v85, v100
	v_cvt_pk_bf16_f32 v100, v112, v113
	v_and_b32_e32 v146, v100, v203
	v_cvt_pk_bf16_f32 v100, v114, v115
	v_and_b32_e32 v147, v100, v203
	ds_read_b64_tr_b16 v[100:101], v196 offset:26624
	ds_read_b64_tr_b16 v[102:103], v196 offset:27136
	s_waitcnt lgkmcnt(13)
	v_mfma_f32_32x32x16_bf16 v[68:83], v[164:167], v[124:127], v[68:83]
	v_add_f32_e32 v108, v86, v108
	v_add_f32_e32 v108, v87, v108
	v_cvt_pk_bf16_f32 v84, v84, v85
	v_add_f32_e32 v108, v88, v108
	v_and_b32_e32 v140, v84, v203
	v_cvt_pk_bf16_f32 v84, v86, v87
	v_add_f32_e32 v108, v89, v108
	v_and_b32_e32 v141, v84, v203
	ds_read_b64_tr_b16 v[84:85], v196 offset:30720
	ds_read_b64_tr_b16 v[86:87], v196 offset:31232
	s_waitcnt lgkmcnt(14)
	v_mfma_f32_32x32x16_bf16 v[52:67], v[160:163], v[124:127], v[52:67]
	v_add_f32_e32 v108, v90, v108
	v_add_f32_e32 v108, v91, v108
	v_cvt_pk_bf16_f32 v88, v88, v89
	v_add_f32_e32 v108, v92, v108
	v_and_b32_e32 v142, v88, v203
	v_cvt_pk_bf16_f32 v88, v90, v91
	v_add_f32_e32 v108, v93, v108
	v_and_b32_e32 v143, v88, v203
	ds_read_b64_tr_b16 v[88:89], v196 offset:27648
	ds_read_b64_tr_b16 v[90:91], v196 offset:28160
	s_waitcnt lgkmcnt(14)
	v_mfma_f32_32x32x16_bf16 v[68:83], v[156:159], v[128:131], v[68:83]
	v_add_f32_e32 v108, v94, v108
	v_add_f32_e32 v108, v95, v108
	v_cvt_pk_bf16_f32 v92, v92, v93
	v_add_f32_e32 v108, v96, v108
	v_and_b32_e32 v136, v92, v203
	v_cvt_pk_bf16_f32 v92, v94, v95
	v_add_f32_e32 v108, v97, v108
	v_and_b32_e32 v137, v92, v203
	ds_read_b64_tr_b16 v[92:93], v196 offset:31744
	ds_read_b64_tr_b16 v[94:95], v196 offset:32256
	v_mfma_f32_32x32x16_bf16 v[52:67], v[152:155], v[128:131], v[52:67]
	v_add_f32_e32 v108, v98, v108
	v_cvt_pk_bf16_f32 v96, v96, v97
	v_add_f32_e32 v108, v99, v108
	v_and_b32_e32 v138, v96, v203
	v_cvt_pk_bf16_f32 v96, v98, v99
	v_and_b32_e32 v139, v96, v203
	s_add_i32 s55, s25, 2
	s_cmp_ge_u32 s55, s48
	s_cselect_b64 s[22:23], -1, 0
	s_and_b64 vcc, exec, s[22:23]
	s_cbranch_vccnz .LBB0_826
	s_add_i32 s0, s42, s46
	s_mov_b32 s1, m0
	s_mov_b32 m0, s0
	s_nop 0
	global_load_lds_dwordx4 v[206:207], off
	s_mov_b32 m0, s1

.LBB0_864:
	s_waitcnt vmcnt(0)
	v_bfe_i32 v133, v132, 0, 1
	v_add_u32_e32 v134, s42, v219
	ds_read_b64_tr_b16 v[100:101], v134 offset:24576
	ds_read_b64_tr_b16 v[102:103], v134 offset:25088
	v_add_f32_e32 v84, v68, v69
	v_add_f32_e32 v84, v70, v84
	v_add_f32_e32 v84, v71, v84
	v_add_f32_e32 v84, v72, v84
	v_add_f32_e32 v108, v73, v84
	s_waitcnt lgkmcnt(9)
	v_mfma_f32_32x32x16_bf16 v[84:99], v[180:183], v[116:119], v[36:51]
	v_cvt_pk_bf16_f32 v68, v68, v69
	v_and_b32_e32 v148, v133, v68
	v_cvt_pk_bf16_f32 v68, v70, v71
	v_and_b32_e32 v149, v133, v68
	ds_read_b64_tr_b16 v[104:105], v134 offset:28672
	ds_read_b64_tr_b16 v[106:107], v134 offset:29184
	s_waitcnt lgkmcnt(10)
	v_mfma_f32_32x32x16_bf16 v[36:51], v[176:179], v[116:119], v[36:51]
	v_add_f32_e32 v68, v74, v108
	v_add_f32_e32 v68, v75, v68
	v_cvt_pk_bf16_f32 v69, v72, v73
	v_add_f32_e32 v68, v76, v68
	v_and_b32_e32 v150, v133, v69
	v_cvt_pk_bf16_f32 v69, v74, v75
	v_add_f32_e32 v68, v77, v68
	v_and_b32_e32 v151, v133, v69
	ds_read_b64_tr_b16 v[108:109], v134 offset:25600
	ds_read_b64_tr_b16 v[110:111], v134 offset:26112
	s_waitcnt lgkmcnt(11)
	v_mfma_f32_32x32x16_bf16 v[84:99], v[172:175], v[120:123], v[84:99]
	v_add_f32_e32 v68, v78, v68
	v_add_f32_e32 v68, v79, v68
	v_cvt_pk_bf16_f32 v69, v76, v77
	v_add_f32_e32 v68, v80, v68
	v_and_b32_e32 v144, v133, v69
	v_cvt_pk_bf16_f32 v69, v78, v79
	v_add_f32_e32 v68, v81, v68
	v_and_b32_e32 v145, v133, v69
	ds_read_b64_tr_b16 v[112:113], v134 offset:29696
	ds_read_b64_tr_b16 v[114:115], v134 offset:30208
	s_waitcnt lgkmcnt(12)
	v_mfma_f32_32x32x16_bf16 v[36:51], v[168:171], v[120:123], v[36:51]
	v_add_f32_e32 v68, v82, v68
	v_add_f32_e32 v68, v83, v68
	v_cvt_pk_bf16_f32 v69, v80, v81
	v_add_f32_e32 v68, v52, v68
	v_and_b32_e32 v146, v133, v69
	v_cvt_pk_bf16_f32 v69, v82, v83
	v_add_f32_e32 v68, v53, v68
	v_and_b32_e32 v147, v133, v69
	ds_read_b64_tr_b16 v[168:169], v134 offset:26624
	ds_read_b64_tr_b16 v[170:171], v134 offset:27136
	s_waitcnt lgkmcnt(13)
	v_mfma_f32_32x32x16_bf16 v[84:99], v[164:167], v[124:127], v[84:99]
	v_add_f32_e32 v68, v54, v68
	v_add_f32_e32 v68, v55, v68
	v_cvt_pk_bf16_f32 v52, v52, v53
	v_add_f32_e32 v68, v56, v68
	v_and_b32_e32 v140, v133, v52
	v_cvt_pk_bf16_f32 v52, v54, v55
	v_add_f32_e32 v68, v57, v68
	v_and_b32_e32 v141, v133, v52
	ds_read_b64_tr_b16 v[164:165], v134 offset:30720
	ds_read_b64_tr_b16 v[166:167], v134 offset:31232
	s_waitcnt lgkmcnt(14)
	v_mfma_f32_32x32x16_bf16 v[36:51], v[160:163], v[124:127], v[36:51]
	v_add_f32_e32 v52, v58, v68
	v_add_f32_e32 v52, v59, v52
	v_cvt_pk_bf16_f32 v53, v56, v57
	v_add_f32_e32 v52, v60, v52
	v_and_b32_e32 v142, v133, v53
	v_cvt_pk_bf16_f32 v53, v58, v59
	v_add_f32_e32 v52, v61, v52
	v_and_b32_e32 v143, v133, v53
	ds_read_b64_tr_b16 v[160:161], v134 offset:27648
	ds_read_b64_tr_b16 v[162:163], v134 offset:28160
	s_waitcnt lgkmcnt(14)
	v_mfma_f32_32x32x16_bf16 v[84:99], v[156:159], v[128:131], v[84:99]
	v_add_f32_e32 v52, v62, v52
	v_add_f32_e32 v52, v63, v52
	v_cvt_pk_bf16_f32 v53, v60, v61
	v_add_f32_e32 v52, v64, v52
	v_and_b32_e32 v136, v133, v53
	v_cvt_pk_bf16_f32 v53, v62, v63
	v_add_f32_e32 v52, v65, v52
	v_and_b32_e32 v137, v133, v53
	ds_read_b64_tr_b16 v[156:157], v134 offset:31744
	ds_read_b64_tr_b16 v[158:159], v134 offset:32256
	v_mfma_f32_32x32x16_bf16 v[36:51], v[152:155], v[128:131], v[36:51]
	v_add_f32_e32 v52, v66, v52
	v_cvt_pk_bf16_f32 v53, v64, v65
	v_add_f32_e32 v52, v67, v52
	v_and_b32_e32 v138, v133, v53
	v_cvt_pk_bf16_f32 v53, v66, v67
	v_and_b32_e32 v139, v133, v53
	v_or_b32_e32 v53, 0xe0, v215
	v_and_b32_e32 v68, v52, v133
	v_or_b32_e32 v52, 0xc0, v215
	v_cmp_le_i32_e32 vcc, v53, v216
	v_or_b32_e32 v54, 0xe1, v215
	v_or_b32_e32 v55, 0xe2, v215
	v_cndmask_b32_e32 v36, v232, v36, vcc
	v_cmp_lt_i32_e32 vcc, v52, v216
	v_or_b32_e32 v56, 0xe3, v215
	v_or_b32_e32 v57, 0xe8, v215
	v_cndmask_b32_e32 v53, v232, v85, vcc
	v_cmp_le_i32_e32 vcc, v52, v216
	v_or_b32_e32 v58, 0xe9, v215
	v_or_b32_e32 v59, 0xea, v215
	v_cndmask_b32_e32 v52, v232, v84, vcc
	v_cmp_le_i32_e32 vcc, v54, v216
	v_or_b32_e32 v54, 0xc2, v215
	v_or_b32_e32 v60, 0xeb, v215
	v_cndmask_b32_e32 v37, v232, v37, vcc
	v_cmp_le_i32_e32 vcc, v54, v216
	v_or_b32_e32 v61, 0xf0, v215
	v_or_b32_e32 v62, 0xf1, v215
	v_cndmask_b32_e32 v54, v232, v86, vcc
	v_cmp_le_i32_e32 vcc, v55, v216
	v_or_b32_e32 v55, 0xc3, v215
	v_or_b32_e32 v63, 0xf2, v215
	v_cndmask_b32_e32 v38, v232, v38, vcc
	v_cmp_le_i32_e32 vcc, v55, v216
	v_or_b32_e32 v64, 0xf3, v215
	v_or_b32_e32 v65, 0xf8, v215
	v_cndmask_b32_e32 v55, v232, v87, vcc
	v_cmp_le_i32_e32 vcc, v56, v216
	v_or_b32_e32 v56, 0xc8, v215
	v_or_b32_e32 v66, 0xf9, v215
	v_cndmask_b32_e32 v39, v232, v39, vcc
	v_cmp_le_i32_e32 vcc, v56, v216
	v_or_b32_e32 v67, 0xfa, v215
	v_or_b32_e32 v69, 0xfb, v215
	v_cndmask_b32_e32 v56, v232, v88, vcc
	v_cmp_le_i32_e32 vcc, v57, v216
	v_or_b32_e32 v57, 0xc9, v215
	v_max_f32_e32 v70, v52, v52
	v_cndmask_b32_e32 v40, v232, v40, vcc
	v_cmp_le_i32_e32 vcc, v57, v216
	v_add_f32_e32 v86, v220, v68
	s_nop 0
	v_cndmask_b32_e32 v57, v232, v89, vcc
	v_cmp_le_i32_e32 vcc, v58, v216
	v_or_b32_e32 v58, 0xca, v215
	s_nop 0
	v_cndmask_b32_e32 v41, v232, v41, vcc
	v_cmp_le_i32_e32 vcc, v58, v216
	s_nop 1
	v_cndmask_b32_e32 v58, v232, v90, vcc
	v_cmp_le_i32_e32 vcc, v59, v216
	v_or_b32_e32 v59, 0xcb, v215
	s_nop 0
	v_cndmask_b32_e32 v42, v232, v42, vcc
	v_cmp_le_i32_e32 vcc, v59, v216
	s_nop 1
	v_cndmask_b32_e32 v59, v232, v91, vcc
	v_cmp_le_i32_e32 vcc, v60, v216
	v_or_b32_e32 v60, 0xd0, v215
	s_nop 0
	v_cndmask_b32_e32 v43, v232, v43, vcc
	v_cmp_le_i32_e32 vcc, v60, v216
	s_nop 1
	v_cndmask_b32_e32 v60, v232, v92, vcc
	v_cmp_le_i32_e32 vcc, v61, v216
	v_or_b32_e32 v61, 0xd1, v215
	s_nop 0
	v_cndmask_b32_e32 v44, v232, v44, vcc
	v_cmp_le_i32_e32 vcc, v61, v216
	s_nop 1
	v_cndmask_b32_e32 v61, v232, v93, vcc
	v_cmp_le_i32_e32 vcc, v62, v216
	v_or_b32_e32 v62, 0xd2, v215
	s_nop 0
	v_cndmask_b32_e32 v45, v232, v45, vcc
	v_cmp_le_i32_e32 vcc, v62, v216
	s_nop 1
	v_cndmask_b32_e32 v62, v232, v94, vcc
	v_cmp_le_i32_e32 vcc, v63, v216
	v_or_b32_e32 v63, 0xd3, v215
	s_nop 0
	v_cndmask_b32_e32 v46, v232, v46, vcc
	v_cmp_le_i32_e32 vcc, v63, v216
	s_nop 1
	v_cndmask_b32_e32 v63, v232, v95, vcc
	v_cmp_le_i32_e32 vcc, v64, v216
	v_or_b32_e32 v64, 0xd8, v215
	s_nop 0
	v_cndmask_b32_e32 v47, v232, v47, vcc
	v_cmp_le_i32_e32 vcc, v64, v216
	s_nop 1
	v_cndmask_b32_e32 v64, v232, v96, vcc
	v_cmp_le_i32_e32 vcc, v65, v216
	v_or_b32_e32 v65, 0xd9, v215
	s_nop 0
	v_cndmask_b32_e32 v48, v232, v48, vcc
	v_cmp_le_i32_e32 vcc, v65, v216
	s_nop 1
	v_cndmask_b32_e32 v65, v232, v97, vcc
	v_cmp_le_i32_e32 vcc, v66, v216
	v_or_b32_e32 v66, 0xda, v215
	s_nop 0
	v_cndmask_b32_e32 v49, v232, v49, vcc
	v_cmp_le_i32_e32 vcc, v66, v216
	s_nop 1
	v_cndmask_b32_e32 v66, v232, v98, vcc
	v_cmp_le_i32_e32 vcc, v67, v216
	v_or_b32_e32 v67, 0xdb, v215
	s_nop 0
	v_cndmask_b32_e32 v50, v232, v50, vcc
	v_cmp_le_i32_e32 vcc, v67, v216
	s_nop 1
	v_cndmask_b32_e32 v67, v232, v99, vcc
	v_cmp_le_i32_e32 vcc, v69, v216
	v_max_f32_e32 v69, v53, v53
	v_max_f32_e32 v69, v70, v69
	v_max3_f32 v70, v54, v55, v37
	v_max3_f32 v69, v69, v36, v38
	v_max3_f32 v69, v69, v39, v56
	v_max3_f32 v70, v70, v58, v59
	v_max3_f32 v69, v69, v57, v40
	v_max3_f32 v70, v70, v42, v43
	v_max3_f32 v69, v69, v41, v60
	v_max3_f32 v70, v70, v62, v63
	v_max3_f32 v69, v69, v61, v44
	v_max3_f32 v70, v70, v46, v47
	v_cndmask_b32_e32 v51, v232, v51, vcc
	v_max3_f32 v69, v69, v45, v64
	v_max3_f32 v70, v70, v66, v67
	v_max3_f32 v69, v69, v65, v48
	v_max3_f32 v70, v70, v50, v51
	v_max3_f32 v68, v69, v49, v70
	v_mov_b32_e32 v69, v68
	s_nop 1
	v_permlane32_swap_b32_e32 v68, v69
	v_max_f32_e32 v69, v69, v69
	v_max_f32_e32 v68, v68, v68
	v_max_f32_e32 v68, v68, v69
	v_cmp_lt_f32_e32 vcc, s33, v68
	s_cmp_lg_u64 vcc, 0
	s_cselect_b64 s[0:1], -1, 0
	s_cbranch_vccnz .LBB0_980

.LBB0_903:
	v_add_u32_e32 v184, s28, v247
	ds_read_b64_tr_b16 v[180:181], v184 offset:24576
	ds_read_b64_tr_b16 v[182:183], v184 offset:25088
	s_waitcnt lgkmcnt(9)
	v_mfma_f32_32x32x16_bf16 v[100:115], v[176:179], v[116:119], v[36:51]
	v_add_f32_e32 v84, v68, v69
	v_add_f32_e32 v84, v70, v84
	v_add_f32_e32 v84, v71, v84
	v_add_f32_e32 v84, v72, v84
	v_add_f32_e32 v84, v73, v84
	v_cvt_pk_bf16_f32 v144, v68, v69
	v_cvt_pk_bf16_f32 v145, v70, v71
	ds_read_b64_tr_b16 v[176:177], v184 offset:28672
	ds_read_b64_tr_b16 v[178:179], v184 offset:29184
	v_add_f32_e32 v68, v74, v84
	s_waitcnt lgkmcnt(10)
	v_mfma_f32_32x32x16_bf16 v[84:99], v[168:171], v[116:119], v[36:51]
	v_add_f32_e32 v68, v75, v68
	v_add_f32_e32 v68, v76, v68
	v_add_f32_e32 v132, v77, v68
	v_cvt_pk_bf16_f32 v146, v72, v73
	v_cvt_pk_bf16_f32 v147, v74, v75
	ds_read_b64_tr_b16 v[68:69], v184 offset:25600
	ds_read_b64_tr_b16 v[70:71], v184 offset:26112
	s_waitcnt lgkmcnt(11)
	v_mfma_f32_32x32x16_bf16 v[100:115], v[172:175], v[120:123], v[100:115]
	v_add_f32_e32 v72, v78, v132
	v_add_f32_e32 v72, v79, v72
	v_add_f32_e32 v72, v80, v72
	v_add_f32_e32 v132, v81, v72
	v_cvt_pk_bf16_f32 v140, v76, v77
	v_cvt_pk_bf16_f32 v141, v78, v79
	ds_read_b64_tr_b16 v[72:73], v184 offset:29696
	ds_read_b64_tr_b16 v[74:75], v184 offset:30208
	s_waitcnt lgkmcnt(12)
	v_mfma_f32_32x32x16_bf16 v[84:99], v[164:167], v[120:123], v[84:99]
	v_add_f32_e32 v76, v82, v132
	v_add_f32_e32 v76, v83, v76
	v_add_f32_e32 v76, v52, v76
	v_add_f32_e32 v132, v53, v76
	v_cvt_pk_bf16_f32 v142, v80, v81
	v_cvt_pk_bf16_f32 v143, v82, v83
	ds_read_b64_tr_b16 v[76:77], v184 offset:26624
	ds_read_b64_tr_b16 v[78:79], v184 offset:27136
	s_waitcnt lgkmcnt(13)
	v_mfma_f32_32x32x16_bf16 v[100:115], v[160:163], v[124:127], v[100:115]
	v_add_f32_e32 v80, v54, v132
	v_add_f32_e32 v80, v55, v80
	v_add_f32_e32 v80, v56, v80
	v_add_f32_e32 v80, v57, v80
	v_cvt_pk_bf16_f32 v136, v52, v53
	v_cvt_pk_bf16_f32 v137, v54, v55
	ds_read_b64_tr_b16 v[52:53], v184 offset:30720
	ds_read_b64_tr_b16 v[54:55], v184 offset:31232
	s_waitcnt lgkmcnt(14)
	v_mfma_f32_32x32x16_bf16 v[84:99], v[156:159], v[124:127], v[84:99]
	v_add_f32_e32 v80, v58, v80
	v_add_f32_e32 v80, v59, v80
	v_add_f32_e32 v80, v60, v80
	v_add_f32_e32 v80, v61, v80
	v_cvt_pk_bf16_f32 v138, v56, v57
	v_cvt_pk_bf16_f32 v139, v58, v59
	ds_read_b64_tr_b16 v[56:57], v184 offset:27648
	ds_read_b64_tr_b16 v[58:59], v184 offset:28160
	s_waitcnt lgkmcnt(14)
	v_mfma_f32_32x32x16_bf16 v[100:115], v[152:155], v[128:131], v[100:115]
	v_add_f32_e32 v80, v62, v80
	v_add_f32_e32 v80, v63, v80
	v_add_f32_e32 v80, v64, v80
	v_add_f32_e32 v80, v65, v80
	v_cvt_pk_bf16_f32 v132, v60, v61
	v_cvt_pk_bf16_f32 v133, v62, v63
	ds_read_b64_tr_b16 v[60:61], v184 offset:31744
	ds_read_b64_tr_b16 v[62:63], v184 offset:32256
	v_mfma_f32_32x32x16_bf16 v[84:99], v[148:151], v[128:131], v[84:99]
	v_add_f32_e32 v80, v66, v80
	v_add_f32_e32 v80, v67, v80
	v_cvt_pk_bf16_f32 v134, v64, v65
	v_cvt_pk_bf16_f32 v135, v66, v67
	s_add_i32 s1, s0, 1
	s_cmp_ge_i32 s1, s51
	s_cselect_b64 s[24:25], -1, 0
	s_and_b64 vcc, exec, s[24:25]
	s_cbranch_vccnz .LBB0_905
	s_add_i32 s1, s53, s49
	s_mov_b32 s26, m0
	s_mov_b32 m0, s1
	s_nop 0
	global_load_lds_dwordx4 v[210:211], off
	s_mov_b32 m0, s26

.LBB0_912:
	v_add_u32_e32 v196, s53, v247
	ds_read_b64_tr_b16 v[188:189], v196 offset:24576
	ds_read_b64_tr_b16 v[190:191], v196 offset:25088
	s_waitcnt lgkmcnt(9)
	v_mfma_f32_32x32x16_bf16 v[68:83], v[176:179], v[116:119], v[36:51]
	v_add_f32_e32 v52, v100, v101
	v_add_f32_e32 v52, v102, v52
	v_add_f32_e32 v52, v103, v52
	v_add_f32_e32 v52, v104, v52
	v_add_f32_e32 v52, v105, v52
	v_cvt_pk_bf16_f32 v144, v100, v101
	v_cvt_pk_bf16_f32 v145, v102, v103
	ds_read_b64_tr_b16 v[184:185], v196 offset:28672
	ds_read_b64_tr_b16 v[186:187], v196 offset:29184
	v_add_f32_e32 v52, v106, v52
	v_add_f32_e32 v52, v107, v52
	v_add_f32_e32 v52, v108, v52
	v_add_f32_e32 v100, v109, v52
	s_waitcnt lgkmcnt(10)
	v_mfma_f32_32x32x16_bf16 v[52:67], v[168:171], v[116:119], v[36:51]
	v_cvt_pk_bf16_f32 v146, v104, v105
	v_cvt_pk_bf16_f32 v147, v106, v107
	ds_read_b64_tr_b16 v[180:181], v196 offset:25600
	ds_read_b64_tr_b16 v[182:183], v196 offset:26112
	s_waitcnt lgkmcnt(11)
	v_mfma_f32_32x32x16_bf16 v[68:83], v[172:175], v[120:123], v[68:83]
	v_add_f32_e32 v100, v110, v100
	v_add_f32_e32 v100, v111, v100
	v_add_f32_e32 v100, v112, v100
	v_add_f32_e32 v100, v113, v100
	v_cvt_pk_bf16_f32 v140, v108, v109
	v_cvt_pk_bf16_f32 v141, v110, v111
	ds_read_b64_tr_b16 v[108:109], v196 offset:29696
	ds_read_b64_tr_b16 v[110:111], v196 offset:30208
	s_waitcnt lgkmcnt(12)
	v_mfma_f32_32x32x16_bf16 v[52:67], v[164:167], v[120:123], v[52:67]
	v_add_f32_e32 v100, v114, v100
	v_add_f32_e32 v100, v115, v100
	v_add_f32_e32 v100, v84, v100
	v_add_f32_e32 v100, v85, v100
	v_cvt_pk_bf16_f32 v142, v112, v113
	v_cvt_pk_bf16_f32 v143, v114, v115
	ds_read_b64_tr_b16 v[104:105], v196 offset:26624
	ds_read_b64_tr_b16 v[106:107], v196 offset:27136
	s_waitcnt lgkmcnt(13)
	v_mfma_f32_32x32x16_bf16 v[68:83], v[160:163], v[124:127], v[68:83]
	v_add_f32_e32 v100, v86, v100
	v_add_f32_e32 v100, v87, v100
	v_add_f32_e32 v100, v88, v100
	v_add_f32_e32 v112, v89, v100
	v_cvt_pk_bf16_f32 v136, v84, v85
	v_cvt_pk_bf16_f32 v137, v86, v87
	ds_read_b64_tr_b16 v[100:101], v196 offset:30720
	ds_read_b64_tr_b16 v[102:103], v196 offset:31232
	s_waitcnt lgkmcnt(14)
	v_mfma_f32_32x32x16_bf16 v[52:67], v[156:159], v[124:127], v[52:67]
	v_add_f32_e32 v84, v90, v112
	v_add_f32_e32 v84, v91, v84
	v_add_f32_e32 v84, v92, v84
	v_add_f32_e32 v84, v93, v84
	v_cvt_pk_bf16_f32 v138, v88, v89
	v_cvt_pk_bf16_f32 v139, v90, v91
	ds_read_b64_tr_b16 v[88:89], v196 offset:27648
	ds_read_b64_tr_b16 v[90:91], v196 offset:28160
	s_waitcnt lgkmcnt(14)
	v_mfma_f32_32x32x16_bf16 v[68:83], v[152:155], v[128:131], v[68:83]
	v_add_f32_e32 v84, v94, v84
	v_add_f32_e32 v84, v95, v84
	v_add_f32_e32 v84, v96, v84
	v_add_f32_e32 v112, v97, v84
	v_cvt_pk_bf16_f32 v132, v92, v93
	v_cvt_pk_bf16_f32 v133, v94, v95
	ds_read_b64_tr_b16 v[84:85], v196 offset:31744
	ds_read_b64_tr_b16 v[86:87], v196 offset:32256
	v_mfma_f32_32x32x16_bf16 v[52:67], v[148:151], v[128:131], v[52:67]
	v_add_f32_e32 v92, v98, v112
	v_add_f32_e32 v92, v99, v92
	v_cvt_pk_bf16_f32 v134, v96, v97
	v_cvt_pk_bf16_f32 v135, v98, v99
	s_add_i32 s26, s0, 2
	s_cmp_ge_i32 s26, s51
	s_cselect_b64 s[28:29], -1, 0
	s_and_b64 vcc, exec, s[28:29]
	s_cbranch_vccnz .LBB0_914
	s_ashr_i32 s27, s26, 31
	s_lshl_b64 s[34:35], s[26:27], 16
	s_add_i32 s1, s54, s49
	v_lshl_add_u64 v[94:95], v[206:207], 0, s[34:35]
	s_mov_b32 s27, m0
	s_mov_b32 m0, s1
	s_nop 0
	global_load_lds_dwordx4 v[94:95], off
	s_mov_b32 m0, s27

.LBB0_953:
	v_add_u32_e32 v188, s28, v247
	ds_read_b64_tr_b16 v[180:181], v188 offset:24576
	ds_read_b64_tr_b16 v[182:183], v188 offset:25088
	s_waitcnt lgkmcnt(9)
	v_mfma_f32_32x32x16_bf16 v[100:115], v[176:179], v[116:119], v[36:51]
	v_add_f32_e32 v84, v68, v69
	v_add_f32_e32 v84, v70, v84
	v_add_f32_e32 v84, v71, v84
	v_add_f32_e32 v84, v72, v84
	v_add_f32_e32 v84, v73, v84
	v_cvt_pk_bf16_f32 v144, v68, v69
	v_cvt_pk_bf16_f32 v145, v70, v71
	ds_read_b64_tr_b16 v[176:177], v188 offset:28672
	ds_read_b64_tr_b16 v[178:179], v188 offset:29184
	v_add_f32_e32 v68, v74, v84
	s_waitcnt lgkmcnt(10)
	v_mfma_f32_32x32x16_bf16 v[84:99], v[168:171], v[116:119], v[36:51]
	v_add_f32_e32 v68, v75, v68
	v_add_f32_e32 v68, v76, v68
	v_add_f32_e32 v132, v77, v68
	v_cvt_pk_bf16_f32 v146, v72, v73
	v_cvt_pk_bf16_f32 v147, v74, v75
	ds_read_b64_tr_b16 v[68:69], v188 offset:25600
	ds_read_b64_tr_b16 v[70:71], v188 offset:26112
	s_waitcnt lgkmcnt(11)
	v_mfma_f32_32x32x16_bf16 v[100:115], v[172:175], v[120:123], v[100:115]
	v_add_f32_e32 v72, v78, v132
	v_add_f32_e32 v72, v79, v72
	v_add_f32_e32 v72, v80, v72
	v_add_f32_e32 v132, v81, v72
	v_cvt_pk_bf16_f32 v140, v76, v77
	v_cvt_pk_bf16_f32 v141, v78, v79
	ds_read_b64_tr_b16 v[72:73], v188 offset:29696
	ds_read_b64_tr_b16 v[74:75], v188 offset:30208
	s_waitcnt lgkmcnt(12)
	v_mfma_f32_32x32x16_bf16 v[84:99], v[164:167], v[120:123], v[84:99]
	v_add_f32_e32 v76, v82, v132
	v_add_f32_e32 v76, v83, v76
	v_add_f32_e32 v76, v52, v76
	v_add_f32_e32 v132, v53, v76
	v_cvt_pk_bf16_f32 v142, v80, v81
	v_cvt_pk_bf16_f32 v143, v82, v83
	ds_read_b64_tr_b16 v[76:77], v188 offset:26624
	ds_read_b64_tr_b16 v[78:79], v188 offset:27136
	s_waitcnt lgkmcnt(13)
	v_mfma_f32_32x32x16_bf16 v[100:115], v[160:163], v[124:127], v[100:115]
	v_add_f32_e32 v80, v54, v132
	v_add_f32_e32 v80, v55, v80
	v_add_f32_e32 v80, v56, v80
	v_add_f32_e32 v80, v57, v80
	v_cvt_pk_bf16_f32 v136, v52, v53
	v_cvt_pk_bf16_f32 v137, v54, v55
	ds_read_b64_tr_b16 v[52:53], v188 offset:30720
	ds_read_b64_tr_b16 v[54:55], v188 offset:31232
	s_waitcnt lgkmcnt(14)
	v_mfma_f32_32x32x16_bf16 v[84:99], v[156:159], v[124:127], v[84:99]
	v_add_f32_e32 v80, v58, v80
	v_add_f32_e32 v80, v59, v80
	v_add_f32_e32 v80, v60, v80
	v_add_f32_e32 v80, v61, v80
	v_cvt_pk_bf16_f32 v138, v56, v57
	v_cvt_pk_bf16_f32 v139, v58, v59
	ds_read_b64_tr_b16 v[56:57], v188 offset:27648
	ds_read_b64_tr_b16 v[58:59], v188 offset:28160
	s_waitcnt lgkmcnt(14)
	v_mfma_f32_32x32x16_bf16 v[100:115], v[152:155], v[128:131], v[100:115]
	v_add_f32_e32 v80, v62, v80
	v_add_f32_e32 v80, v63, v80
	v_add_f32_e32 v80, v64, v80
	v_add_f32_e32 v80, v65, v80
	v_cvt_pk_bf16_f32 v132, v60, v61
	v_cvt_pk_bf16_f32 v133, v62, v63
	ds_read_b64_tr_b16 v[60:61], v188 offset:31744
	ds_read_b64_tr_b16 v[62:63], v188 offset:32256
	v_mfma_f32_32x32x16_bf16 v[84:99], v[148:151], v[128:131], v[84:99]
	v_add_f32_e32 v80, v66, v80
	v_add_f32_e32 v80, v67, v80
	v_cvt_pk_bf16_f32 v134, v64, v65
	v_cvt_pk_bf16_f32 v135, v66, v67
	v_lshl_add_u64 v[188:189], v[184:185], 0, s[0:1]
	v_lshl_add_u64 v[64:65], v[188:189], 0, s[54:55]
	s_add_i32 s26, s31, s49
	s_mov_b32 s27, m0
	s_mov_b32 m0, s26
	s_nop 0
	global_load_lds_dwordx4 v[64:65], off
	s_mov_b32 m0, s27
	v_lshl_add_u64 v[190:191], v[186:187], 0, s[0:1]
	s_mov_b64 s[26:27], 0x10000
	v_lshl_add_u64 v[64:65], v[190:191], 0, s[26:27]
	s_add_i32 s26, s30, s50
	s_mov_b32 s27, m0
	s_mov_b32 m0, s26
	s_nop 0
	global_load_lds_dwordx4 v[64:65], off
	s_mov_b32 m0, s27
	v_add_f32_e32 v195, v248, v80
.LBB0_954:
	s_waitcnt lgkmcnt(14)
	v_mfma_f32_32x32x16_bf16 v[20:35], v[144:147], v[180:183], v[20:35]
	v_exp_f32_e32 v100, v100
	v_exp_f32_e32 v101, v101
	v_exp_f32_e32 v102, v102
	v_exp_f32_e32 v103, v103
	s_waitcnt lgkmcnt(12)
	v_mfma_f32_32x32x16_bf16 v[4:19], v[144:147], v[176:179], v[4:19]
	v_exp_f32_e32 v104, v104
	v_exp_f32_e32 v105, v105
	v_exp_f32_e32 v106, v106
	v_exp_f32_e32 v107, v107
	v_add_u32_e32 v80, s30, v246
	ds_read_b128 v[64:67], v80
	ds_read_b128 v[176:179], v80 offset:512
	s_waitcnt lgkmcnt(12)
	v_mfma_f32_32x32x16_bf16 v[20:35], v[140:143], v[68:71], v[20:35]
	v_exp_f32_e32 v108, v108
	v_exp_f32_e32 v109, v109
	v_exp_f32_e32 v110, v110
	v_exp_f32_e32 v111, v111
	ds_read_b128 v[180:183], v80 offset:2048
	ds_read_b128 v[172:175], v80 offset:2560
	s_waitcnt lgkmcnt(12)
	v_mfma_f32_32x32x16_bf16 v[4:19], v[140:143], v[72:75], v[4:19]
	v_exp_f32_e32 v112, v112
	v_exp_f32_e32 v113, v113
	v_exp_f32_e32 v114, v114
	v_exp_f32_e32 v115, v115
	ds_read_b128 v[168:171], v80 offset:4096
	ds_read_b128 v[164:167], v80 offset:4608
	s_waitcnt lgkmcnt(12)
	v_mfma_f32_32x32x16_bf16 v[20:35], v[136:139], v[76:79], v[20:35]
	v_exp_f32_e32 v84, v84
	v_exp_f32_e32 v85, v85
	v_exp_f32_e32 v86, v86
	v_exp_f32_e32 v87, v87
	ds_read_b128 v[160:163], v80 offset:6144
	ds_read_b128 v[156:159], v80 offset:6656
	s_waitcnt lgkmcnt(12)
	v_mfma_f32_32x32x16_bf16 v[4:19], v[136:139], v[52:55], v[4:19]
	v_exp_f32_e32 v88, v88
	v_exp_f32_e32 v89, v89
	v_exp_f32_e32 v90, v90
	v_exp_f32_e32 v91, v91
	s_waitcnt lgkmcnt(10)
	v_mfma_f32_32x32x16_bf16 v[20:35], v[132:135], v[56:59], v[20:35]
	v_exp_f32_e32 v92, v92
	v_exp_f32_e32 v93, v93
	v_exp_f32_e32 v94, v94
	v_exp_f32_e32 v95, v95
	s_waitcnt lgkmcnt(8)
	v_mfma_f32_32x32x16_bf16 v[4:19], v[132:135], v[60:63], v[4:19]
	v_exp_f32_e32 v96, v96
	v_exp_f32_e32 v97, v97
	v_exp_f32_e32 v98, v98
	v_exp_f32_e32 v99, v99
	s_waitcnt vmcnt(2) lgkmcnt(0)
	s_barrier
	v_add_u32_e32 v194, s48, v192
.LBB0_956:
	s_add_i32 s26, s30, 0x2000
	s_cmpk_lg_i32 s30, 0x4000
	s_cselect_b32 s53, s26, 0
	v_add_u32_e32 v196, s31, v247
	ds_read_b64_tr_b16 v[152:153], v196 offset:24576
	ds_read_b64_tr_b16 v[154:155], v196 offset:25088
	s_waitcnt lgkmcnt(9)
	v_mfma_f32_32x32x16_bf16 v[68:83], v[64:67], v[116:119], v[36:51]
	v_add_f32_e32 v52, v100, v101
	v_add_f32_e32 v52, v102, v52
	v_add_f32_e32 v52, v103, v52
	v_add_f32_e32 v52, v104, v52
	v_add_f32_e32 v52, v105, v52
	v_cvt_pk_bf16_f32 v144, v100, v101
	v_cvt_pk_bf16_f32 v145, v102, v103
	ds_read_b64_tr_b16 v[148:149], v196 offset:28672
	ds_read_b64_tr_b16 v[150:151], v196 offset:29184
	v_add_f32_e32 v52, v106, v52
	v_add_f32_e32 v52, v107, v52
	v_add_f32_e32 v52, v108, v52
	v_add_f32_e32 v132, v109, v52
	s_waitcnt lgkmcnt(10)
	v_mfma_f32_32x32x16_bf16 v[52:67], v[176:179], v[116:119], v[36:51]
	v_cvt_pk_bf16_f32 v146, v104, v105
	v_cvt_pk_bf16_f32 v147, v106, v107
	ds_read_b64_tr_b16 v[100:101], v196 offset:25600
	ds_read_b64_tr_b16 v[102:103], v196 offset:26112
	s_waitcnt lgkmcnt(11)
	v_mfma_f32_32x32x16_bf16 v[68:83], v[180:183], v[120:123], v[68:83]
	v_add_f32_e32 v104, v110, v132
	v_add_f32_e32 v104, v111, v104
	v_add_f32_e32 v104, v112, v104
	v_add_f32_e32 v132, v113, v104
	v_cvt_pk_bf16_f32 v140, v108, v109
	v_cvt_pk_bf16_f32 v141, v110, v111
	ds_read_b64_tr_b16 v[104:105], v196 offset:29696
	ds_read_b64_tr_b16 v[106:107], v196 offset:30208
	s_waitcnt lgkmcnt(12)
	v_mfma_f32_32x32x16_bf16 v[52:67], v[172:175], v[120:123], v[52:67]
	v_add_f32_e32 v108, v114, v132
	v_add_f32_e32 v108, v115, v108
	v_add_f32_e32 v108, v84, v108
	v_add_f32_e32 v132, v85, v108
	v_cvt_pk_bf16_f32 v142, v112, v113
	v_cvt_pk_bf16_f32 v143, v114, v115
	ds_read_b64_tr_b16 v[108:109], v196 offset:26624
	ds_read_b64_tr_b16 v[110:111], v196 offset:27136
	s_waitcnt lgkmcnt(13)
	v_mfma_f32_32x32x16_bf16 v[68:83], v[168:171], v[124:127], v[68:83]
	v_add_f32_e32 v112, v86, v132
	v_add_f32_e32 v112, v87, v112
	v_add_f32_e32 v112, v88, v112
	v_add_f32_e32 v112, v89, v112
	v_cvt_pk_bf16_f32 v136, v84, v85
	v_cvt_pk_bf16_f32 v137, v86, v87
	ds_read_b64_tr_b16 v[84:85], v196 offset:30720
	ds_read_b64_tr_b16 v[86:87], v196 offset:31232
	s_waitcnt lgkmcnt(14)
	v_mfma_f32_32x32x16_bf16 v[52:67], v[164:167], v[124:127], v[52:67]
	v_add_f32_e32 v112, v90, v112
	v_add_f32_e32 v112, v91, v112
	v_add_f32_e32 v112, v92, v112
	v_add_f32_e32 v112, v93, v112
	v_cvt_pk_bf16_f32 v138, v88, v89
	v_cvt_pk_bf16_f32 v139, v90, v91
	ds_read_b64_tr_b16 v[88:89], v196 offset:27648
	ds_read_b64_tr_b16 v[90:91], v196 offset:28160
	s_waitcnt lgkmcnt(14)
	v_mfma_f32_32x32x16_bf16 v[68:83], v[160:163], v[128:131], v[68:83]
	v_add_f32_e32 v112, v94, v112
	v_add_f32_e32 v112, v95, v112
	v_add_f32_e32 v112, v96, v112
	v_add_f32_e32 v112, v97, v112
	v_cvt_pk_bf16_f32 v132, v92, v93
	v_cvt_pk_bf16_f32 v133, v94, v95
	ds_read_b64_tr_b16 v[92:93], v196 offset:31744
	ds_read_b64_tr_b16 v[94:95], v196 offset:32256
	v_mfma_f32_32x32x16_bf16 v[52:67], v[156:159], v[128:131], v[52:67]
	v_add_f32_e32 v112, v98, v112
	v_add_f32_e32 v112, v99, v112
	v_cvt_pk_bf16_f32 v134, v96, v97
	v_cvt_pk_bf16_f32 v135, v98, v99
	v_lshl_add_u64 v[96:97], v[188:189], 0, s[80:81]
	s_add_i32 s26, s30, s49
	s_mov_b32 s27, m0
	s_mov_b32 m0, s26
	s_nop 0
	global_load_lds_dwordx4 v[96:97], off
	s_mov_b32 m0, s27
	s_mov_b64 s[26:27], 0x20000
	v_lshl_add_u64 v[96:97], v[190:191], 0, s[26:27]
	s_add_i32 s26, s53, s50
	s_mov_b32 s27, m0
	s_mov_b32 m0, s26
	s_nop 0
	global_load_lds_dwordx4 v[96:97], off
	s_mov_b32 m0, s27
	v_add_f32_e32 v248, v195, v112
.LBB0_957:
	s_waitcnt lgkmcnt(14)
	v_mfma_f32_32x32x16_bf16 v[20:35], v[144:147], v[152:155], v[20:35]
	v_exp_f32_e32 v68, v68
	v_exp_f32_e32 v69, v69
	v_exp_f32_e32 v70, v70
	v_exp_f32_e32 v71, v71
	s_waitcnt lgkmcnt(12)
	v_mfma_f32_32x32x16_bf16 v[4:19], v[144:147], v[148:151], v[4:19]
	v_exp_f32_e32 v72, v72
	v_exp_f32_e32 v73, v73
	v_exp_f32_e32 v74, v74
	v_exp_f32_e32 v75, v75
	v_add_u32_e32 v96, s53, v246
	ds_read_b128 v[176:179], v96
	ds_read_b128 v[168:171], v96 offset:512
	s_waitcnt lgkmcnt(12)
	v_mfma_f32_32x32x16_bf16 v[20:35], v[140:143], v[100:103], v[20:35]
	v_exp_f32_e32 v76, v76
	v_exp_f32_e32 v77, v77
	v_exp_f32_e32 v78, v78
	v_exp_f32_e32 v79, v79
	ds_read_b128 v[172:175], v96 offset:2048
	ds_read_b128 v[164:167], v96 offset:2560
	s_waitcnt lgkmcnt(12)
	v_mfma_f32_32x32x16_bf16 v[4:19], v[140:143], v[104:107], v[4:19]
	v_exp_f32_e32 v80, v80
	v_exp_f32_e32 v81, v81
	v_exp_f32_e32 v82, v82
	v_exp_f32_e32 v83, v83
	ds_read_b128 v[160:163], v96 offset:4096
	ds_read_b128 v[156:159], v96 offset:4608
	s_waitcnt lgkmcnt(12)
	v_mfma_f32_32x32x16_bf16 v[20:35], v[136:139], v[108:111], v[20:35]
	v_exp_f32_e32 v52, v52
	v_exp_f32_e32 v53, v53
	v_exp_f32_e32 v54, v54
	v_exp_f32_e32 v55, v55
	ds_read_b128 v[152:155], v96 offset:6144
	ds_read_b128 v[148:151], v96 offset:6656
	s_waitcnt lgkmcnt(12)
	v_mfma_f32_32x32x16_bf16 v[4:19], v[136:139], v[84:87], v[4:19]
	v_exp_f32_e32 v56, v56
	v_exp_f32_e32 v57, v57
	v_exp_f32_e32 v58, v58
	v_exp_f32_e32 v59, v59
	s_waitcnt lgkmcnt(10)
	v_mfma_f32_32x32x16_bf16 v[20:35], v[132:135], v[88:91], v[20:35]
	v_exp_f32_e32 v60, v60
	v_exp_f32_e32 v61, v61
	v_exp_f32_e32 v62, v62
	v_exp_f32_e32 v63, v63
	s_waitcnt lgkmcnt(8)
	v_mfma_f32_32x32x16_bf16 v[4:19], v[132:135], v[92:95], v[4:19]
	v_exp_f32_e32 v64, v64
	v_exp_f32_e32 v65, v65
	v_exp_f32_e32 v66, v66
	v_exp_f32_e32 v67, v67
	s_waitcnt vmcnt(2) lgkmcnt(0)
	s_barrier
.LBB0_959:
	s_add_i32 s26, s25, 2
	s_add_i32 s27, s53, 0x2000
	s_cmpk_lg_i32 s53, 0x4000
	s_cselect_b32 s54, s27, 0
	s_add_i32 s25, s25, 7
	s_mov_b64 s[28:29], 0x20000
	v_lshl_add_u64 v[186:187], v[186:187], 0, s[28:29]
	s_cmp_ge_i32 s25, s51
	v_lshl_add_u64 v[184:185], v[184:185], 0, s[28:29]
	s_mov_b32 s28, s30
	s_cbranch_scc1 .LBB0_901
	s_mov_b32 s31, s53
	s_mov_b32 s30, s54
	s_mov_b32 s25, s26
	s_mov_b64 s[54:55], 0x30000
	s_branch .LBB0_953
